# v53 plus fox skip-bound loads merged into one round trip
# baseline (speedup 1.0000x reference)
; __device__ __forceinline__ int mk_lane() { int l = (int)__builtin_amdgcn_mbcnt_hi(~0u, __builtin_amdgcn_mbcnt_lo(~0u, 0u)); asm volatile("" : "+v"(l)); return l; }
; __global__ void __launch_bounds__(NWAVES * 64, 2) mk_fwd(Params P) {
;     ...
;                 } else { if (!(MK_ATT_MASK & 2)) continue; const int h = hm;
;                     const float* nq = NRM + ((b * 2 + 0) * 8 + h) * 2; const float* nk = NRM + ((b * 2 + 1) * 8 + h) * 2; const float* kbr = KBIAS + (size_t)(b * 8 + h) * SEQ;
;                     const float bqk = sqrtf((nq[0] + nq[1]) * (nk[0] + nk[1])) * 1.02f;
;                     const int NTf = 4 * qb + 4, tc = 2 * (mk_lane() & 31);
;                     const bool skip_ok = (tc >= 2) && (tc <= NTf - 4) && (2.f * bqk + kbr[64 * tc - 1 + (tc ? 0 : 1)] - kbr[256 * qb] < -40.f);
;                     const unsigned long long bm = __ballot(skip_ok);
;                     const int t0 = bm ? 2 * ((63 - __builtin_clzll(bm)) & 31) : 0;
.LBB0_519:
	s_and_b64 s[0:1], s[84:85], exec
	s_cselect_b32 s78, s92, s76
	s_and_b64 vcc, exec, s[46:47]
	s_mov_b64 s[0:1], -1
	s_cbranch_vccz .LBB0_601
	global_load_dwordx2 v[4:5], v1, s[48:49]
	global_load_dwordx2 v[2:3], v1, s[48:49] offset:64
	v_mov_b32_e32 v0, v212
	s_lshl_b32 s80, s78, 2
	v_lshlrev_b32_e32 v0, 1, v0
	v_and_b32_e32 v0, 62, v0
	v_add_u32_e32 v6, -1, v0
	v_cmp_le_u32_e32 vcc, s80, v6
	s_and_saveexec_b64 s[0:1], vcc
	s_xor_b64 s[0:1], exec, s[0:1]
	s_lshl_b32 s2, s78, 8
	s_or_saveexec_b64 s[4:5], s[0:1]
	s_mov_b64 s[0:1], 0
	v_mov_b32_e32 v199, s2
	s_xor_b64 exec, exec, s[4:5]
	s_cbranch_execz .LBB0_524
	v_lshlrev_b32_e32 v0, 8, v0
	global_load_dword v0, v0, s[50:51] offset:-4
	v_lshlrev_b32_e64 v8, 10, s78
	global_load_dword v8, v8, s[50:51]
	s_waitcnt vmcnt(3)
	v_mov_b32_e32 v6, v4
	s_waitcnt vmcnt(2)
	v_mov_b32_e32 v7, v2
	v_mov_b32_e32 v2, v5
	v_pk_add_f32 v[2:3], v[6:7], v[2:3]
	s_nop 0
	v_mul_f32_e32 v2, v2, v3
	v_cmp_gt_f32_e32 vcc, s64, v2
	v_mul_f32_e32 v3, 0x4f800000, v2
	s_nop 0
	v_cndmask_b32_e32 v2, v2, v3, vcc
	v_sqrt_f32_e32 v3, v2
	s_nop 0
	v_add_u32_e32 v4, -1, v3
	v_fma_f32 v5, -v4, v3, v2
	v_cmp_ge_f32_e64 s[0:1], 0, v5
	v_add_u32_e32 v5, 1, v3
	s_nop 0
	v_cndmask_b32_e64 v4, v3, v4, s[0:1]
	v_fma_f32 v3, -v5, v3, v2
	v_cmp_lt_f32_e64 s[0:1], 0, v3
	s_nop 1
	v_cndmask_b32_e64 v3, v4, v5, s[0:1]
	v_mul_f32_e32 v4, 0x37800000, v3
	v_cndmask_b32_e32 v3, v3, v4, vcc
	v_cmp_class_f32_e32 vcc, v2, v213
	s_lshl_b32 s1, s78, 10
	s_lshl_b32 s0, s78, 8
	v_cndmask_b32_e32 v2, v3, v2, vcc
	v_mul_f32_e32 v2, 0x3f828f5c, v2
	v_mov_b32_e32 v199, s0
	s_waitcnt vmcnt(0)
	v_fmac_f32_e32 v0, 2.0, v2
	v_mov_b32_e32 v2, v8
	s_mov_b32 s1, 0xc2200000
	v_sub_f32_e32 v0, v0, v2
	v_cmp_gt_f32_e32 vcc, s1, v0
	s_and_b64 s[0:1], vcc, exec
